# P8 SwiGLU epilogue: sigmoid reciprocal via v_rcp_f32 (f32, 1 ulp) instead of the 10-instruction IEEE division expansion; dead feeder code removed
# speedup vs baseline: 1.0886x; 1.0096x over previous
.Ltk0_bit:
	s_or_b32 s48, s12, s32
	s_or_b32 s71, s13, s32
	s_or_b32 s73, s14, s32
	s_or_b32 s75, s15, s32
	v_cmp_le_i32_e64 s[6:7], s48, v33
	v_cmp_le_i32_e64 s[8:9], s71, v34
	v_cmp_le_i32_e64 s[20:21], s73, v35
	v_cmp_le_i32_e64 s[24:25], s75, v36
	s_bcnt1_i32_b64 s23, s[6:7]
	s_cmp_ge_u32 s23, 16
	s_cselect_b32 s12, s48, s12
	s_bcnt1_i32_b64 s23, s[8:9]
	s_cmp_ge_u32 s23, 16
	s_cselect_b32 s13, s71, s13
	s_bcnt1_i32_b64 s23, s[20:21]
	s_cmp_ge_u32 s23, 16
	s_cselect_b32 s14, s73, s14
	s_bcnt1_i32_b64 s23, s[24:25]
	s_cmp_ge_u32 s23, 16
	s_cselect_b32 s15, s75, s15
	s_or_b32 s48, s16, s32
	s_or_b32 s71, s17, s32
	s_or_b32 s73, s18, s32
	s_or_b32 s75, s19, s32
	v_cmp_le_i32_e64 s[6:7], s48, v37
	v_cmp_le_i32_e64 s[8:9], s71, v38
	v_cmp_le_i32_e64 s[20:21], s73, v39
	v_cmp_le_i32_e64 s[24:25], s75, v40
	s_bcnt1_i32_b64 s23, s[6:7]
	s_cmp_ge_u32 s23, 16
	s_cselect_b32 s16, s48, s16
	s_bcnt1_i32_b64 s23, s[8:9]
	s_cmp_ge_u32 s23, 16
	s_cselect_b32 s17, s71, s17
	s_bcnt1_i32_b64 s23, s[20:21]
	s_cmp_ge_u32 s23, 16
	s_cselect_b32 s18, s73, s18
	s_bcnt1_i32_b64 s23, s[24:25]
	s_cmp_ge_u32 s23, 16
	s_cselect_b32 s19, s75, s19
	s_lshr_b32 s32, s32, 1
	s_cmp_lg_u32 s32, 0
	s_cbranch_scc1 .Ltk0_bit
	v_cmp_lt_i32_e64 s[6:7], s12, v33
	v_cmp_eq_i32_e64 s[8:9], s12, v33
	v_cmp_eq_u32_e64 s[20:21], 0, v128
	s_bcnt1_i32_b64 s23, s[6:7]
	s_sub_i32 s23, 16, s23
.Ltk0_tie0:
	s_ff1_i32_b64 s48, s[8:9]
	s_bitset1_b64 s[6:7], s48
	s_bitset0_b64 s[8:9], s48
	s_sub_i32 s23, s23, 1
	s_cmp_gt_i32 s23, 0
	s_cbranch_scc1 .Ltk0_tie0
	v_mov_b32_e32 v41, s6
	v_mov_b32_e32 v42, s7
	v_cndmask_b32_e64 v140, v140, v41, s[20:21]
	v_cndmask_b32_e64 v141, v141, v42, s[20:21]
	v_cmp_lt_i32_e64 s[6:7], s13, v34
	v_cmp_eq_i32_e64 s[8:9], s13, v34
	v_cmp_eq_u32_e64 s[20:21], 1, v128
	s_bcnt1_i32_b64 s23, s[6:7]
	s_sub_i32 s23, 16, s23
.Ltk0_tie1:
	s_ff1_i32_b64 s48, s[8:9]
	s_bitset1_b64 s[6:7], s48
	s_bitset0_b64 s[8:9], s48
	s_sub_i32 s23, s23, 1
	s_cmp_gt_i32 s23, 0
	s_cbranch_scc1 .Ltk0_tie1
	v_mov_b32_e32 v41, s6
	v_mov_b32_e32 v42, s7
	v_cndmask_b32_e64 v140, v140, v41, s[20:21]
	v_cndmask_b32_e64 v141, v141, v42, s[20:21]
	v_cmp_lt_i32_e64 s[6:7], s14, v35
	v_cmp_eq_i32_e64 s[8:9], s14, v35
	v_cmp_eq_u32_e64 s[20:21], 2, v128
	s_bcnt1_i32_b64 s23, s[6:7]
	s_sub_i32 s23, 16, s23
.Ltk0_tie2:
	s_ff1_i32_b64 s48, s[8:9]
	s_bitset1_b64 s[6:7], s48
	s_bitset0_b64 s[8:9], s48
	s_sub_i32 s23, s23, 1
	s_cmp_gt_i32 s23, 0
	s_cbranch_scc1 .Ltk0_tie2
	v_mov_b32_e32 v41, s6
	v_mov_b32_e32 v42, s7
	v_cndmask_b32_e64 v140, v140, v41, s[20:21]
	v_cndmask_b32_e64 v141, v141, v42, s[20:21]
	v_cmp_lt_i32_e64 s[6:7], s15, v36
	v_cmp_eq_i32_e64 s[8:9], s15, v36
	v_cmp_eq_u32_e64 s[20:21], 3, v128
	s_bcnt1_i32_b64 s23, s[6:7]
	s_sub_i32 s23, 16, s23
.Ltk0_tie3:
	s_ff1_i32_b64 s48, s[8:9]
	s_bitset1_b64 s[6:7], s48
	s_bitset0_b64 s[8:9], s48
	s_sub_i32 s23, s23, 1
	s_cmp_gt_i32 s23, 0
	s_cbranch_scc1 .Ltk0_tie3
	v_mov_b32_e32 v41, s6
	v_mov_b32_e32 v42, s7
	v_cndmask_b32_e64 v140, v140, v41, s[20:21]
	v_cndmask_b32_e64 v141, v141, v42, s[20:21]
	v_cmp_lt_i32_e64 s[6:7], s16, v37
	v_cmp_eq_i32_e64 s[8:9], s16, v37
	v_cmp_eq_u32_e64 s[20:21], 4, v128
	s_bcnt1_i32_b64 s23, s[6:7]
	s_sub_i32 s23, 16, s23
.Ltk0_tie4:
	s_ff1_i32_b64 s48, s[8:9]
	s_bitset1_b64 s[6:7], s48
	s_bitset0_b64 s[8:9], s48
	s_sub_i32 s23, s23, 1
	s_cmp_gt_i32 s23, 0
	s_cbranch_scc1 .Ltk0_tie4
	v_mov_b32_e32 v41, s6
	v_mov_b32_e32 v42, s7
	v_cndmask_b32_e64 v140, v140, v41, s[20:21]
	v_cndmask_b32_e64 v141, v141, v42, s[20:21]
	v_cmp_lt_i32_e64 s[6:7], s17, v38
	v_cmp_eq_i32_e64 s[8:9], s17, v38
	v_cmp_eq_u32_e64 s[20:21], 5, v128
	s_bcnt1_i32_b64 s23, s[6:7]
	s_sub_i32 s23, 16, s23
.Ltk0_tie5:
	s_ff1_i32_b64 s48, s[8:9]
	s_bitset1_b64 s[6:7], s48
	s_bitset0_b64 s[8:9], s48
	s_sub_i32 s23, s23, 1
	s_cmp_gt_i32 s23, 0
	s_cbranch_scc1 .Ltk0_tie5
	v_mov_b32_e32 v41, s6
	v_mov_b32_e32 v42, s7
	v_cndmask_b32_e64 v140, v140, v41, s[20:21]
	v_cndmask_b32_e64 v141, v141, v42, s[20:21]
	v_cmp_lt_i32_e64 s[6:7], s18, v39
	v_cmp_eq_i32_e64 s[8:9], s18, v39
	v_cmp_eq_u32_e64 s[20:21], 6, v128
	s_bcnt1_i32_b64 s23, s[6:7]
	s_sub_i32 s23, 16, s23
.Ltk0_tie6:
	s_ff1_i32_b64 s48, s[8:9]
	s_bitset1_b64 s[6:7], s48
	s_bitset0_b64 s[8:9], s48
	s_sub_i32 s23, s23, 1
	s_cmp_gt_i32 s23, 0
	s_cbranch_scc1 .Ltk0_tie6
	v_mov_b32_e32 v41, s6
	v_mov_b32_e32 v42, s7
	v_cndmask_b32_e64 v140, v140, v41, s[20:21]
	v_cndmask_b32_e64 v141, v141, v42, s[20:21]
	v_cmp_lt_i32_e64 s[6:7], s19, v40
	v_cmp_eq_i32_e64 s[8:9], s19, v40
	v_cmp_eq_u32_e64 s[20:21], 7, v128
	s_bcnt1_i32_b64 s23, s[6:7]
	s_sub_i32 s23, 16, s23
.Ltk0_tie7:
	s_ff1_i32_b64 s48, s[8:9]
	s_bitset1_b64 s[6:7], s48
	s_bitset0_b64 s[8:9], s48
	s_sub_i32 s23, s23, 1
	s_cmp_gt_i32 s23, 0
	s_cbranch_scc1 .Ltk0_tie7
	v_mov_b32_e32 v41, s6
	v_mov_b32_e32 v42, s7
	v_cndmask_b32_e64 v140, v140, v41, s[20:21]
	v_cndmask_b32_e64 v141, v141, v42, s[20:21]
	v_mov_b32_e32 v33, 0x4e6e6b28
	v_mov_b32_e32 v34, 0x4e6e6b28
	v_mov_b32_e32 v35, 0x4e6e6b28
	v_mov_b32_e32 v36, 0x4e6e6b28
	v_mov_b32_e32 v37, 0x4e6e6b28
	v_mov_b32_e32 v38, 0x4e6e6b28
	v_mov_b32_e32 v39, 0x4e6e6b28
	v_mov_b32_e32 v40, 0x4e6e6b28
	s_and_b64 exec, s[26:27], s[10:11]
	ds_read_b32 v33, v131 offset:2048
	ds_read_b32 v34, v131 offset:2304
	ds_read_b32 v35, v131 offset:2560
	ds_read_b32 v36, v131 offset:2816
	ds_read_b32 v37, v131 offset:3072
	ds_read_b32 v38, v131 offset:3328
	ds_read_b32 v39, v131 offset:3584
	ds_read_b32 v40, v131 offset:3840
	s_waitcnt lgkmcnt(0)
	v_cndmask_b32_e64 v33, v165, v33, s[76:77]
	v_cndmask_b32_e64 v34, v165, v34, s[76:77]
	v_cndmask_b32_e64 v35, v165, v35, s[76:77]
	v_cndmask_b32_e64 v36, v165, v36, s[76:77]
	v_cndmask_b32_e64 v37, v165, v37, s[76:77]
	v_cndmask_b32_e64 v38, v165, v38, s[76:77]
	v_cndmask_b32_e64 v39, v165, v39, s[76:77]
	v_cndmask_b32_e64 v40, v165, v40, s[76:77]
	s_mov_b64 exec, s[26:27]
	s_mov_b32 s12, 0
	s_mov_b32 s13, 0
	s_mov_b32 s14, 0
	s_mov_b32 s15, 0
	s_mov_b32 s16, 0
	s_mov_b32 s17, 0
	s_mov_b32 s18, 0
	s_mov_b32 s19, 0
	s_mov_b32 s32, 0x40000000
.Ltk8_bit:
	s_or_b32 s48, s12, s32
	s_or_b32 s71, s13, s32
	s_or_b32 s73, s14, s32
	s_or_b32 s75, s15, s32
	v_cmp_le_i32_e64 s[6:7], s48, v33
	v_cmp_le_i32_e64 s[8:9], s71, v34
	v_cmp_le_i32_e64 s[20:21], s73, v35
	v_cmp_le_i32_e64 s[24:25], s75, v36
	s_bcnt1_i32_b64 s23, s[6:7]
	s_cmp_ge_u32 s23, 16
	s_cselect_b32 s12, s48, s12
	s_bcnt1_i32_b64 s23, s[8:9]
	s_cmp_ge_u32 s23, 16
	s_cselect_b32 s13, s71, s13
	s_bcnt1_i32_b64 s23, s[20:21]
	s_cmp_ge_u32 s23, 16
	s_cselect_b32 s14, s73, s14
	s_bcnt1_i32_b64 s23, s[24:25]
	s_cmp_ge_u32 s23, 16
	s_cselect_b32 s15, s75, s15
	s_or_b32 s48, s16, s32
	s_or_b32 s71, s17, s32
	s_or_b32 s73, s18, s32
	s_or_b32 s75, s19, s32
	v_cmp_le_i32_e64 s[6:7], s48, v37
	v_cmp_le_i32_e64 s[8:9], s71, v38
	v_cmp_le_i32_e64 s[20:21], s73, v39
	v_cmp_le_i32_e64 s[24:25], s75, v40
	s_bcnt1_i32_b64 s23, s[6:7]
	s_cmp_ge_u32 s23, 16
	s_cselect_b32 s16, s48, s16
	s_bcnt1_i32_b64 s23, s[8:9]
	s_cmp_ge_u32 s23, 16
	s_cselect_b32 s17, s71, s17
	s_bcnt1_i32_b64 s23, s[20:21]
	s_cmp_ge_u32 s23, 16
	s_cselect_b32 s18, s73, s18
	s_bcnt1_i32_b64 s23, s[24:25]
	s_cmp_ge_u32 s23, 16
	s_cselect_b32 s19, s75, s19
	s_lshr_b32 s32, s32, 1
	s_cmp_lg_u32 s32, 0
	s_cbranch_scc1 .Ltk8_bit
	v_cmp_lt_i32_e64 s[6:7], s12, v33
	v_cmp_eq_i32_e64 s[8:9], s12, v33
	v_cmp_eq_u32_e64 s[20:21], 8, v128
	s_bcnt1_i32_b64 s23, s[6:7]
	s_sub_i32 s23, 16, s23
.Ltk8_tie0:
	s_ff1_i32_b64 s48, s[8:9]
	s_bitset1_b64 s[6:7], s48
	s_bitset0_b64 s[8:9], s48
	s_sub_i32 s23, s23, 1
	s_cmp_gt_i32 s23, 0
	s_cbranch_scc1 .Ltk8_tie0
	v_mov_b32_e32 v41, s6
	v_mov_b32_e32 v42, s7
	v_cndmask_b32_e64 v140, v140, v41, s[20:21]
	v_cndmask_b32_e64 v141, v141, v42, s[20:21]
	v_cmp_lt_i32_e64 s[6:7], s13, v34
	v_cmp_eq_i32_e64 s[8:9], s13, v34
	v_cmp_eq_u32_e64 s[20:21], 9, v128
	s_bcnt1_i32_b64 s23, s[6:7]
	s_sub_i32 s23, 16, s23
.Ltk8_tie1:
	s_ff1_i32_b64 s48, s[8:9]
	s_bitset1_b64 s[6:7], s48
	s_bitset0_b64 s[8:9], s48
	s_sub_i32 s23, s23, 1
	s_cmp_gt_i32 s23, 0
	s_cbranch_scc1 .Ltk8_tie1
	v_mov_b32_e32 v41, s6
	v_mov_b32_e32 v42, s7
	v_cndmask_b32_e64 v140, v140, v41, s[20:21]
	v_cndmask_b32_e64 v141, v141, v42, s[20:21]
	v_cmp_lt_i32_e64 s[6:7], s14, v35
	v_cmp_eq_i32_e64 s[8:9], s14, v35
	v_cmp_eq_u32_e64 s[20:21], 10, v128
	s_bcnt1_i32_b64 s23, s[6:7]
	s_sub_i32 s23, 16, s23
.Ltk8_tie2:
	s_ff1_i32_b64 s48, s[8:9]
	s_bitset1_b64 s[6:7], s48
	s_bitset0_b64 s[8:9], s48
	s_sub_i32 s23, s23, 1
	s_cmp_gt_i32 s23, 0
	s_cbranch_scc1 .Ltk8_tie2
	v_mov_b32_e32 v41, s6
	v_mov_b32_e32 v42, s7
	v_cndmask_b32_e64 v140, v140, v41, s[20:21]
	v_cndmask_b32_e64 v141, v141, v42, s[20:21]
	v_cmp_lt_i32_e64 s[6:7], s15, v36
	v_cmp_eq_i32_e64 s[8:9], s15, v36
	v_cmp_eq_u32_e64 s[20:21], 11, v128
	s_bcnt1_i32_b64 s23, s[6:7]
	s_sub_i32 s23, 16, s23
.Ltk8_tie3:
	s_ff1_i32_b64 s48, s[8:9]
	s_bitset1_b64 s[6:7], s48
	s_bitset0_b64 s[8:9], s48
	s_sub_i32 s23, s23, 1
	s_cmp_gt_i32 s23, 0
	s_cbranch_scc1 .Ltk8_tie3
	v_mov_b32_e32 v41, s6
	v_mov_b32_e32 v42, s7
	v_cndmask_b32_e64 v140, v140, v41, s[20:21]
	v_cndmask_b32_e64 v141, v141, v42, s[20:21]
	v_cmp_lt_i32_e64 s[6:7], s16, v37
	v_cmp_eq_i32_e64 s[8:9], s16, v37
	v_cmp_eq_u32_e64 s[20:21], 12, v128
	s_bcnt1_i32_b64 s23, s[6:7]
	s_sub_i32 s23, 16, s23
.Ltk8_tie4:
	s_ff1_i32_b64 s48, s[8:9]
	s_bitset1_b64 s[6:7], s48
	s_bitset0_b64 s[8:9], s48
	s_sub_i32 s23, s23, 1
	s_cmp_gt_i32 s23, 0
	s_cbranch_scc1 .Ltk8_tie4
	v_mov_b32_e32 v41, s6
	v_mov_b32_e32 v42, s7
	v_cndmask_b32_e64 v140, v140, v41, s[20:21]
	v_cndmask_b32_e64 v141, v141, v42, s[20:21]
	v_cmp_lt_i32_e64 s[6:7], s17, v38
	v_cmp_eq_i32_e64 s[8:9], s17, v38
	v_cmp_eq_u32_e64 s[20:21], 13, v128
	s_bcnt1_i32_b64 s23, s[6:7]
	s_sub_i32 s23, 16, s23
.Ltk8_tie5:
	s_ff1_i32_b64 s48, s[8:9]
	s_bitset1_b64 s[6:7], s48
	s_bitset0_b64 s[8:9], s48
	s_sub_i32 s23, s23, 1
	s_cmp_gt_i32 s23, 0
	s_cbranch_scc1 .Ltk8_tie5
	v_mov_b32_e32 v41, s6
	v_mov_b32_e32 v42, s7
	v_cndmask_b32_e64 v140, v140, v41, s[20:21]
	v_cndmask_b32_e64 v141, v141, v42, s[20:21]
	v_cmp_lt_i32_e64 s[6:7], s18, v39
	v_cmp_eq_i32_e64 s[8:9], s18, v39
	v_cmp_eq_u32_e64 s[20:21], 14, v128
	s_bcnt1_i32_b64 s23, s[6:7]
	s_sub_i32 s23, 16, s23
.Ltk8_tie6:
	s_ff1_i32_b64 s48, s[8:9]
	s_bitset1_b64 s[6:7], s48
	s_bitset0_b64 s[8:9], s48
	s_sub_i32 s23, s23, 1
	s_cmp_gt_i32 s23, 0
	s_cbranch_scc1 .Ltk8_tie6
	v_mov_b32_e32 v41, s6
	v_mov_b32_e32 v42, s7
	v_cndmask_b32_e64 v140, v140, v41, s[20:21]
	v_cndmask_b32_e64 v141, v141, v42, s[20:21]
	v_cmp_lt_i32_e64 s[6:7], s19, v40
	v_cmp_eq_i32_e64 s[8:9], s19, v40
	v_cmp_eq_u32_e64 s[20:21], 15, v128
	s_bcnt1_i32_b64 s23, s[6:7]
	s_sub_i32 s23, 16, s23
.Ltk8_tie7:
	s_ff1_i32_b64 s48, s[8:9]
	s_bitset1_b64 s[6:7], s48
	s_bitset0_b64 s[8:9], s48
	s_sub_i32 s23, s23, 1
	s_cmp_gt_i32 s23, 0
	s_cbranch_scc1 .Ltk8_tie7
	v_mov_b32_e32 v41, s6
	v_mov_b32_e32 v42, s7
	v_cndmask_b32_e64 v140, v140, v41, s[20:21]
	v_cndmask_b32_e64 v141, v141, v42, s[20:21]
	s_mov_b64 s[6:7], 0

.LBB0_550:
	v_lshl_add_u32 v144, s8, 8, v146
	v_ashrrev_i32_e32 v145, 31, v144
	v_lshlrev_b64 v[154:155], 6, v[144:145]
	v_lshl_add_u64 v[166:167], s[40:41], 0, v[154:155]
	global_load_dwordx4 v[154:157], v[166:167], off
	global_load_dwordx4 v[158:161], v[166:167], off offset:16
	global_load_dwordx4 v[162:165], v[166:167], off offset:32
	s_nop 0
	global_load_dwordx4 v[166:169], v[166:167], off offset:48
	v_mov_b32_e32 v173, v120
	v_mov_b32_e32 v120, v125
	v_mov_b32_e32 v125, v122
	v_mov_b32_e32 v172, v124
	v_mov_b32_e32 v124, v126
	v_lshl_or_b32 v170, s0, 7, v148
	v_ashrrev_i32_e32 v171, 31, v170
	s_waitcnt vmcnt(0)
	v_mov_b32_e32 v174, v155
	v_mov_b32_e32 v175, v156
	v_mov_b32_e32 v155, v157
	v_mov_b32_e32 v156, v159
	v_mov_b32_e32 v157, v160
	v_mov_b32_e32 v159, v161
	v_pk_add_f32 v[154:155], v[174:175], v[154:155]
	v_pk_add_f32 v[156:157], v[156:157], v[158:159]
	v_pk_add_f32 v[154:155], v[154:155], v[154:155] op_sel:[0,1] op_sel_hi:[1,0]
	v_pk_add_f32 v[156:157], v[156:157], v[156:157] op_sel:[0,1] op_sel_hi:[1,0]
	v_add_f32_e32 v160, v162, v163
	v_add_f32_e32 v162, v164, v165
	v_mov_b32_e32 v161, v168
	v_mov_b32_e32 v163, v169
	v_mov_b32_e32 v155, v166
	v_mov_b32_e32 v157, v167
	v_pk_add_f32 v[158:159], v[160:161], v[162:163]
	v_pk_add_f32 v[154:155], v[154:155], v[156:157]
	s_nop 0
	v_pk_add_f32 v[154:155], v[154:155], v[158:159]
	s_nop 0
	v_add_f32_e32 v122, v154, v155
	v_fmamk_f32 v122, v122, 0x3a800000, v152
	v_mul_f32_e32 v126, 0x4b800000, v122
	v_cmp_gt_f32_e32 vcc, s58, v122
	s_nop 1
	v_cndmask_b32_e32 v122, v122, v126, vcc
	v_rsq_f32_e32 v145, v122
	v_mov_b32_e32 v126, v112
	v_mov_b32_e32 v122, v127
	v_mul_f32_e32 v112, 0x45800000, v145
	v_cndmask_b32_e32 v112, v145, v112, vcc
	v_pk_mul_f32 v[154:155], v[172:173], v[112:113] op_sel_hi:[1,0]
	v_pk_mul_f32 v[120:121], v[120:121], v[112:113] op_sel_hi:[1,0]
	v_mul_f32_e32 v127, 0xbfb8aa3b, v155
	v_pk_mul_f32 v[124:125], v[124:125], v[112:113] op_sel_hi:[1,0]
	v_mul_f32_e32 v145, 0xbfb8aa3b, v121
	v_exp_f32_e32 v127, v127
	v_mul_f32_e32 v153, 0xbfb8aa3b, v125
	v_exp_f32_e32 v145, v145
	v_exp_f32_e32 v153, v153
	v_add_f32_e32 v127, 1.0, v127
	v_add_f32_e32 v145, 1.0, v145
	v_add_f32_e32 v153, 1.0, v153
	v_pk_mul_f32 v[122:123], v[122:123], v[112:113] op_sel_hi:[1,0]
	v_mul_f32_e32 v156, 0xbfb8aa3b, v123
	v_exp_f32_e32 v156, v156
	s_nop 0
	v_add_f32_e32 v156, 1.0, v156
	v_rcp_f32_e32 v127, v127
	s_nop 0
	v_mul_f32_e32 v127, v155, v127
	v_rcp_f32_e32 v145, v145
	s_nop 0
	v_mul_f32_e32 v121, v121, v145
	v_rcp_f32_e32 v145, v153
	v_mul_f32_e32 v127, v154, v127
	v_mul_f32_e32 v120, v120, v121
	v_mul_f32_e32 v121, v125, v145
	v_mul_f32_e32 v121, v124, v121
	v_cvt_pk_bf16_f32 v124, v127, v120
	v_mov_b32_e32 v127, v116
	v_pk_mul_f32 v[126:127], v[126:127], v[112:113] op_sel_hi:[1,0]
	v_mul_f32_e32 v116, 0xbfb8aa3b, v127
	v_exp_f32_e32 v116, v116
	s_nop 0
	v_add_f32_e32 v145, 1.0, v116
	v_rcp_f32_e32 v125, v156
	s_nop 0
	v_mul_f32_e32 v123, v123, v125
	v_mul_f32_e32 v120, v122, v123
	v_cvt_pk_bf16_f32 v125, v121, v120
	v_mov_b64_e32 v[120:121], s[34:35]
	v_mad_i64_i32 v[154:155], s[0:1], v144, s59, v[120:121]
	v_lshlrev_b64 v[122:123], 1, v[170:171]
	v_lshl_add_u64 v[154:155], v[154:155], 0, v[122:123]
	global_store_dwordx2 v[154:155], v[124:125], off
	v_mov_b32_e32 v116, v113
	v_pk_mul_f32 v[116:117], v[116:117], v[112:113] op_sel_hi:[1,0]
	v_mul_f32_e32 v113, 0xbfb8aa3b, v117
	v_exp_f32_e32 v113, v113
	v_rcp_f32_e32 v124, v145
	s_nop 0
	v_mul_f32_e32 v124, v127, v124
	v_add_f32_e32 v113, 1.0, v113
	v_mul_f32_e32 v126, v126, v124
	v_mov_b32_e32 v124, v114
	v_mov_b32_e32 v125, v118
	v_pk_mul_f32 v[124:125], v[124:125], v[112:113] op_sel_hi:[1,0]
	v_mul_f32_e32 v114, 0xbfb8aa3b, v125
	v_exp_f32_e32 v114, v114
	v_rcp_f32_e32 v113, v113
	s_nop 0
	v_mul_f32_e32 v113, v117, v113
	v_add_f32_e32 v114, 1.0, v114
	v_div_scale_f32 v127, s[0:1], v114, v114, 1.0
	v_rcp_f32_e32 v145, v127
	v_mul_f32_e32 v116, v116, v113
	v_div_scale_f32 v117, vcc, 1.0, v114, 1.0
	v_fma_f32 v113, -v127, v145, 1.0
	v_fmac_f32_e32 v145, v113, v145
	v_mul_f32_e32 v153, v117, v145
	v_fma_f32 v113, -v127, v153, v117
	v_mov_b32_e32 v118, v115
	v_pk_mul_f32 v[112:113], v[118:119], v[112:113] op_sel_hi:[1,0]
	v_mul_f32_e32 v115, 0xbfb8aa3b, v113
	v_exp_f32_e32 v115, v115
	v_rcp_f32_e32 v114, v114
	s_nop 0
	v_mul_f32_e32 v114, v125, v114
	v_add_f32_e32 v115, 1.0, v115
	v_mul_f32_e32 v114, v124, v114
	v_or_b32_e32 v158, 16, v144
	v_ashrrev_i32_e32 v159, 31, v158
	v_div_scale_f32 v117, vcc, 1.0, v115, 1.0
	v_rcp_f32_e32 v115, v115
	s_nop 0
	v_mul_f32_e32 v113, v113, v115
	v_mul_f32_e32 v113, v112, v113
	v_cvt_pk_bf16_f32 v112, v126, v116
	v_cvt_pk_bf16_f32 v113, v114, v113
	global_store_dwordx2 v[154:155], v[112:113], off offset:128
	v_lshlrev_b64 v[112:113], 6, v[158:159]
	v_lshl_add_u64 v[154:155], s[40:41], 0, v[112:113]
	global_load_dwordx4 v[112:115], v[154:155], off
	global_load_dwordx4 v[116:119], v[154:155], off offset:16
	global_load_dwordx4 v[124:127], v[154:155], off offset:32
	s_nop 0
	global_load_dwordx4 v[154:157], v[154:155], off offset:48
	s_waitcnt vmcnt(3)
	v_mov_b32_e32 v160, v113
	v_mov_b32_e32 v161, v114
	v_mov_b32_e32 v113, v115
	s_waitcnt vmcnt(2)
	v_mov_b32_e32 v114, v117
	v_mov_b32_e32 v115, v118
	v_mov_b32_e32 v117, v119
	v_pk_add_f32 v[112:113], v[160:161], v[112:113]
	v_pk_add_f32 v[114:115], v[114:115], v[116:117]
	v_pk_add_f32 v[112:113], v[112:113], v[112:113] op_sel:[0,1] op_sel_hi:[1,0]
	v_pk_add_f32 v[114:115], v[114:115], v[114:115] op_sel:[0,1] op_sel_hi:[1,0]
	s_waitcnt vmcnt(1)
	v_add_f32_e32 v116, v124, v125
	v_add_f32_e32 v118, v126, v127
	s_waitcnt vmcnt(0)
	v_mov_b32_e32 v113, v154
	v_mov_b32_e32 v115, v155
	v_mov_b32_e32 v117, v156
	v_mov_b32_e32 v119, v157
	v_pk_add_f32 v[112:113], v[112:113], v[114:115]
	v_pk_add_f32 v[114:115], v[116:117], v[118:119]
	s_nop 0
	v_pk_add_f32 v[112:113], v[112:113], v[114:115]
	v_mov_b32_e32 v114, v104
	v_add_f32_e32 v112, v112, v113
	v_fmamk_f32 v112, v112, 0x3a800000, v152
	v_mul_f32_e32 v113, 0x4b800000, v112
	v_cmp_gt_f32_e32 vcc, s58, v112
	v_mov_b32_e32 v115, v108
	v_mov_b32_e32 v108, v105
	v_cndmask_b32_e32 v112, v112, v113, vcc
	v_rsq_f32_e32 v112, v112
	s_nop 0
	v_mul_f32_e32 v113, 0x45800000, v112
	v_cndmask_b32_e32 v112, v112, v113, vcc
	v_pk_mul_f32 v[114:115], v[114:115], v[112:113] op_sel_hi:[1,0]
	s_nop 0
	v_mul_f32_e32 v104, 0xbfb8aa3b, v115
	v_exp_f32_e32 v104, v104
	s_nop 0
	v_add_f32_e32 v113, 1.0, v104
	v_pk_mul_f32 v[104:105], v[108:109], v[112:113] op_sel_hi:[1,0]
	v_mul_f32_e32 v108, 0xbfb8aa3b, v105
	v_exp_f32_e32 v108, v108
	s_nop 0
	v_add_f32_e32 v116, 1.0, v108
	v_rcp_f32_e32 v108, v113
	s_nop 0
	v_mul_f32_e32 v108, v115, v108
	v_mul_f32_e32 v113, v114, v108
	v_mov_b32_e32 v108, v106
	v_mov_b32_e32 v109, v110
	v_pk_mul_f32 v[108:109], v[108:109], v[112:113] op_sel_hi:[1,0]
	v_mul_f32_e32 v106, 0xbfb8aa3b, v109
	v_exp_f32_e32 v106, v106
	v_rcp_f32_e32 v110, v116
	s_nop 0
	v_mul_f32_e32 v105, v105, v110
	v_add_f32_e32 v106, 1.0, v106
	v_mul_f32_e32 v116, v104, v105
	v_mov_b32_e32 v110, v107
	v_pk_mul_f32 v[104:105], v[110:111], v[112:113] op_sel_hi:[1,0]
	v_mul_f32_e32 v107, 0xbfb8aa3b, v105
	v_exp_f32_e32 v107, v107
	v_rcp_f32_e32 v106, v106
	s_nop 0
	v_mul_f32_e32 v106, v109, v106
	v_add_f32_e32 v107, 1.0, v107
	v_mul_f32_e32 v108, v108, v106
	v_rcp_f32_e32 v106, v107
	s_nop 0
	v_mul_f32_e32 v105, v105, v106
	v_mov_b32_e32 v106, v96
	v_mov_b32_e32 v107, v100
	v_pk_mul_f32 v[106:107], v[106:107], v[112:113] op_sel_hi:[1,0]
	v_mul_f32_e32 v100, v104, v105
	v_mul_f32_e32 v96, 0xbfb8aa3b, v107
	v_exp_f32_e32 v96, v96
	v_cvt_pk_bf16_f32 v104, v113, v116
	v_cvt_pk_bf16_f32 v105, v108, v100
	v_mad_i64_i32 v[108:109], s[0:1], v158, s59, v[120:121]
	v_add_f32_e32 v110, 1.0, v96
	v_div_scale_f32 v111, s[0:1], v110, v110, 1.0
	v_rcp_f32_e32 v113, v111
	v_lshl_add_u64 v[108:109], v[108:109], 0, v[122:123]
	global_store_dwordx2 v[108:109], v[104:105], off
	v_fma_f32 v96, -v111, v113, 1.0
	v_fmac_f32_e32 v113, v96, v113
	v_mov_b32_e32 v100, v97
	v_pk_mul_f32 v[96:97], v[100:101], v[112:113] op_sel_hi:[1,0]
	v_mul_f32_e32 v100, 0xbfb8aa3b, v97
	v_exp_f32_e32 v100, v100
	s_nop 0
	v_add_f32_e32 v104, 1.0, v100
	v_rcp_f32_e32 v100, v110
	s_nop 0
	v_mul_f32_e32 v100, v107, v100
	v_mul_f32_e32 v106, v106, v100
	v_mov_b32_e32 v100, v98
	v_mov_b32_e32 v101, v102
	v_pk_mul_f32 v[100:101], v[100:101], v[112:113] op_sel_hi:[1,0]
	v_mul_f32_e32 v98, 0xbfb8aa3b, v101
	v_exp_f32_e32 v98, v98
	v_rcp_f32_e32 v102, v104
	s_nop 0
	v_mul_f32_e32 v97, v97, v102
	v_add_f32_e32 v98, 1.0, v98
	v_mul_f32_e32 v104, v96, v97
	v_mov_b32_e32 v102, v99
	v_pk_mul_f32 v[96:97], v[102:103], v[112:113] op_sel_hi:[1,0]
	v_mul_f32_e32 v99, 0xbfb8aa3b, v97
	v_exp_f32_e32 v99, v99
	v_rcp_f32_e32 v98, v98
	s_nop 0
	v_mul_f32_e32 v98, v101, v98
	v_add_f32_e32 v99, 1.0, v99
	v_mul_f32_e32 v98, v100, v98
	v_or_b32_e32 v112, 32, v144
	v_ashrrev_i32_e32 v113, 31, v112
	v_div_scale_f32 v100, vcc, 1.0, v99, 1.0
	v_rcp_f32_e32 v99, v99
	s_nop 0
	v_mul_f32_e32 v97, v97, v99
	v_mul_f32_e32 v97, v96, v97
	v_cvt_pk_bf16_f32 v96, v106, v104
	v_cvt_pk_bf16_f32 v97, v98, v97
	global_store_dwordx2 v[108:109], v[96:97], off offset:128
	v_lshlrev_b64 v[96:97], 6, v[112:113]
	v_lshl_add_u64 v[108:109], s[40:41], 0, v[96:97]
	global_load_dwordx4 v[96:99], v[108:109], off
	global_load_dwordx4 v[100:103], v[108:109], off offset:16
	global_load_dwordx4 v[104:107], v[108:109], off offset:32
	s_nop 0
	global_load_dwordx4 v[108:111], v[108:109], off offset:48
	s_waitcnt vmcnt(3)
	v_mov_b32_e32 v114, v97
	v_mov_b32_e32 v115, v98
	v_mov_b32_e32 v97, v99
	s_waitcnt vmcnt(2)
	v_mov_b32_e32 v98, v101
	v_mov_b32_e32 v99, v102
	v_mov_b32_e32 v101, v103
	v_pk_add_f32 v[96:97], v[114:115], v[96:97]
	v_pk_add_f32 v[98:99], v[98:99], v[100:101]
	v_pk_add_f32 v[96:97], v[96:97], v[96:97] op_sel:[0,1] op_sel_hi:[1,0]
	v_pk_add_f32 v[98:99], v[98:99], v[98:99] op_sel:[0,1] op_sel_hi:[1,0]
	s_waitcnt vmcnt(1)
	v_add_f32_e32 v100, v104, v105
	v_add_f32_e32 v102, v106, v107
	s_waitcnt vmcnt(0)
	v_mov_b32_e32 v97, v108
	v_mov_b32_e32 v99, v109
	v_mov_b32_e32 v101, v110
	v_mov_b32_e32 v103, v111
	v_pk_add_f32 v[96:97], v[96:97], v[98:99]
	v_pk_add_f32 v[98:99], v[100:101], v[102:103]
	s_nop 0
	v_pk_add_f32 v[96:97], v[96:97], v[98:99]
	v_mov_b32_e32 v98, v88
	v_add_f32_e32 v96, v96, v97
	v_fmamk_f32 v96, v96, 0x3a800000, v152
	v_mul_f32_e32 v97, 0x4b800000, v96
	v_cmp_gt_f32_e32 vcc, s58, v96
	v_mov_b32_e32 v99, v92
	v_mov_b32_e32 v92, v89
	v_cndmask_b32_e32 v96, v96, v97, vcc
	v_rsq_f32_e32 v96, v96
	s_nop 0
	v_mul_f32_e32 v97, 0x45800000, v96
	v_cndmask_b32_e32 v96, v96, v97, vcc
	v_pk_mul_f32 v[98:99], v[98:99], v[96:97] op_sel_hi:[1,0]
	s_nop 0
	v_mul_f32_e32 v88, 0xbfb8aa3b, v99
	v_exp_f32_e32 v88, v88
	s_nop 0
	v_add_f32_e32 v97, 1.0, v88
	v_pk_mul_f32 v[88:89], v[92:93], v[96:97] op_sel_hi:[1,0]
	v_mul_f32_e32 v92, 0xbfb8aa3b, v89
	v_exp_f32_e32 v92, v92
	s_nop 0
	v_add_f32_e32 v100, 1.0, v92
	v_rcp_f32_e32 v92, v97
	s_nop 0
	v_mul_f32_e32 v92, v99, v92
	v_mul_f32_e32 v97, v98, v92
	v_mov_b32_e32 v92, v90
	v_mov_b32_e32 v93, v94
	v_pk_mul_f32 v[92:93], v[92:93], v[96:97] op_sel_hi:[1,0]
	v_mul_f32_e32 v90, 0xbfb8aa3b, v93
	v_exp_f32_e32 v90, v90
	v_rcp_f32_e32 v94, v100
	s_nop 0
	v_mul_f32_e32 v89, v89, v94
	v_add_f32_e32 v90, 1.0, v90
	v_mul_f32_e32 v100, v88, v89
	v_mov_b32_e32 v94, v91
	v_pk_mul_f32 v[88:89], v[94:95], v[96:97] op_sel_hi:[1,0]
	v_mul_f32_e32 v91, 0xbfb8aa3b, v89
	v_exp_f32_e32 v91, v91
	v_rcp_f32_e32 v90, v90
	s_nop 0
	v_mul_f32_e32 v90, v93, v90
	v_add_f32_e32 v91, 1.0, v91
	v_mul_f32_e32 v92, v92, v90
	v_rcp_f32_e32 v90, v91
	s_nop 0
	v_mul_f32_e32 v89, v89, v90
	v_mov_b32_e32 v90, v80
	v_mov_b32_e32 v91, v84
	v_pk_mul_f32 v[90:91], v[90:91], v[96:97] op_sel_hi:[1,0]
	v_mul_f32_e32 v84, v88, v89
	v_mul_f32_e32 v80, 0xbfb8aa3b, v91
	v_exp_f32_e32 v80, v80
	v_cvt_pk_bf16_f32 v88, v97, v100
	v_cvt_pk_bf16_f32 v89, v92, v84
	v_mad_i64_i32 v[92:93], s[0:1], v112, s59, v[120:121]
	v_add_f32_e32 v94, 1.0, v80
	v_div_scale_f32 v95, s[0:1], v94, v94, 1.0
	v_rcp_f32_e32 v97, v95
	v_lshl_add_u64 v[92:93], v[92:93], 0, v[122:123]
	global_store_dwordx2 v[92:93], v[88:89], off
	v_fma_f32 v80, -v95, v97, 1.0
	v_fmac_f32_e32 v97, v80, v97
	v_mov_b32_e32 v84, v81
	v_pk_mul_f32 v[80:81], v[84:85], v[96:97] op_sel_hi:[1,0]
	v_mul_f32_e32 v84, 0xbfb8aa3b, v81
	v_exp_f32_e32 v84, v84
	s_nop 0
	v_add_f32_e32 v88, 1.0, v84
	v_rcp_f32_e32 v84, v94
	s_nop 0
	v_mul_f32_e32 v84, v91, v84
	v_mul_f32_e32 v90, v90, v84
	v_mov_b32_e32 v84, v82
	v_mov_b32_e32 v85, v86
	v_pk_mul_f32 v[84:85], v[84:85], v[96:97] op_sel_hi:[1,0]
	v_mul_f32_e32 v82, 0xbfb8aa3b, v85
	v_exp_f32_e32 v82, v82
	v_rcp_f32_e32 v86, v88
	s_nop 0
	v_mul_f32_e32 v81, v81, v86
	v_add_f32_e32 v82, 1.0, v82
	v_mul_f32_e32 v88, v80, v81
	v_mov_b32_e32 v86, v83
	v_pk_mul_f32 v[80:81], v[86:87], v[96:97] op_sel_hi:[1,0]
	v_mul_f32_e32 v83, 0xbfb8aa3b, v81
	v_exp_f32_e32 v83, v83
	v_rcp_f32_e32 v82, v82
	s_nop 0
	v_mul_f32_e32 v82, v85, v82
	v_add_f32_e32 v83, 1.0, v83
	v_mul_f32_e32 v82, v84, v82
	v_or_b32_e32 v96, 48, v144
	v_ashrrev_i32_e32 v97, 31, v96
	v_div_scale_f32 v84, vcc, 1.0, v83, 1.0
	v_rcp_f32_e32 v83, v83
	s_nop 0
	v_mul_f32_e32 v81, v81, v83
	v_mul_f32_e32 v81, v80, v81
	v_cvt_pk_bf16_f32 v80, v90, v88
	v_cvt_pk_bf16_f32 v81, v82, v81
	global_store_dwordx2 v[92:93], v[80:81], off offset:128
	v_lshlrev_b64 v[80:81], 6, v[96:97]
	v_lshl_add_u64 v[98:99], s[40:41], 0, v[80:81]
	global_load_dwordx4 v[80:83], v[98:99], off
	global_load_dwordx4 v[84:87], v[98:99], off offset:16
	global_load_dwordx4 v[88:91], v[98:99], off offset:32
	global_load_dwordx4 v[92:95], v[98:99], off offset:48
	s_waitcnt vmcnt(3)
	v_mov_b32_e32 v98, v81
	v_mov_b32_e32 v99, v82
	v_mov_b32_e32 v81, v83
	s_waitcnt vmcnt(2)
	v_mov_b32_e32 v82, v85
	v_mov_b32_e32 v83, v86
	v_mov_b32_e32 v85, v87
	v_pk_add_f32 v[80:81], v[98:99], v[80:81]
	v_pk_add_f32 v[82:83], v[82:83], v[84:85]
	v_pk_add_f32 v[80:81], v[80:81], v[80:81] op_sel:[0,1] op_sel_hi:[1,0]
	v_pk_add_f32 v[82:83], v[82:83], v[82:83] op_sel:[0,1] op_sel_hi:[1,0]
	s_waitcnt vmcnt(1)
	v_add_f32_e32 v84, v88, v89
	v_add_f32_e32 v86, v90, v91
	s_waitcnt vmcnt(0)
	v_mov_b32_e32 v81, v92
	v_mov_b32_e32 v83, v93
	v_mov_b32_e32 v85, v94
	v_mov_b32_e32 v87, v95
	v_pk_add_f32 v[80:81], v[80:81], v[82:83]
	v_pk_add_f32 v[82:83], v[84:85], v[86:87]
	s_nop 0
	v_pk_add_f32 v[80:81], v[80:81], v[82:83]
	v_mov_b32_e32 v82, v72
	v_add_f32_e32 v80, v80, v81
	v_fmamk_f32 v80, v80, 0x3a800000, v152
	v_mul_f32_e32 v81, 0x4b800000, v80
	v_cmp_gt_f32_e32 vcc, s58, v80
	v_mov_b32_e32 v83, v76
	v_mov_b32_e32 v76, v73
	v_cndmask_b32_e32 v80, v80, v81, vcc
	v_rsq_f32_e32 v80, v80
	s_nop 0
	v_mul_f32_e32 v81, 0x45800000, v80
	v_cndmask_b32_e32 v80, v80, v81, vcc
	v_pk_mul_f32 v[82:83], v[82:83], v[80:81] op_sel_hi:[1,0]
	s_nop 0
	v_mul_f32_e32 v72, 0xbfb8aa3b, v83
	v_exp_f32_e32 v72, v72
	s_nop 0
	v_add_f32_e32 v81, 1.0, v72
	v_pk_mul_f32 v[72:73], v[76:77], v[80:81] op_sel_hi:[1,0]
	v_mul_f32_e32 v76, 0xbfb8aa3b, v73
	v_exp_f32_e32 v76, v76
	s_nop 0
	v_add_f32_e32 v84, 1.0, v76
	v_rcp_f32_e32 v76, v81
	s_nop 0
	v_mul_f32_e32 v76, v83, v76
	v_mul_f32_e32 v81, v82, v76
	v_mov_b32_e32 v76, v74
	v_mov_b32_e32 v77, v78
	v_pk_mul_f32 v[76:77], v[76:77], v[80:81] op_sel_hi:[1,0]
	v_mul_f32_e32 v74, 0xbfb8aa3b, v77
	v_exp_f32_e32 v74, v74
	v_rcp_f32_e32 v78, v84
	s_nop 0
	v_mul_f32_e32 v73, v73, v78
	v_add_f32_e32 v74, 1.0, v74
	v_mul_f32_e32 v84, v72, v73
	v_mov_b32_e32 v78, v75
	v_pk_mul_f32 v[72:73], v[78:79], v[80:81] op_sel_hi:[1,0]
	v_mul_f32_e32 v75, 0xbfb8aa3b, v73
	v_exp_f32_e32 v75, v75
	v_rcp_f32_e32 v74, v74
	s_nop 0
	v_mul_f32_e32 v74, v77, v74
	v_add_f32_e32 v75, 1.0, v75
	v_mul_f32_e32 v76, v76, v74
	v_rcp_f32_e32 v74, v75
	s_nop 0
	v_mul_f32_e32 v73, v73, v74
	v_mov_b32_e32 v74, v64
	v_mov_b32_e32 v75, v68
	v_pk_mul_f32 v[74:75], v[74:75], v[80:81] op_sel_hi:[1,0]
	v_mul_f32_e32 v68, v72, v73
	v_mul_f32_e32 v64, 0xbfb8aa3b, v75
	v_exp_f32_e32 v64, v64
	v_cvt_pk_bf16_f32 v72, v81, v84
	v_cvt_pk_bf16_f32 v73, v76, v68
	v_mad_i64_i32 v[76:77], s[0:1], v96, s59, v[120:121]
	v_add_f32_e32 v78, 1.0, v64
	v_div_scale_f32 v79, s[0:1], v78, v78, 1.0
	v_rcp_f32_e32 v81, v79
	v_lshl_add_u64 v[76:77], v[76:77], 0, v[122:123]
	global_store_dwordx2 v[76:77], v[72:73], off
	v_fma_f32 v64, -v79, v81, 1.0
	v_fmac_f32_e32 v81, v64, v81
	v_mov_b32_e32 v68, v65
	v_pk_mul_f32 v[64:65], v[68:69], v[80:81] op_sel_hi:[1,0]
	v_mul_f32_e32 v68, 0xbfb8aa3b, v65
	v_exp_f32_e32 v68, v68
	s_nop 0
	v_add_f32_e32 v72, 1.0, v68
	v_rcp_f32_e32 v68, v78
	s_nop 0
	v_mul_f32_e32 v68, v75, v68
	v_mul_f32_e32 v74, v74, v68
	v_mov_b32_e32 v68, v66
	v_mov_b32_e32 v69, v70
	v_pk_mul_f32 v[68:69], v[68:69], v[80:81] op_sel_hi:[1,0]
	v_mul_f32_e32 v66, 0xbfb8aa3b, v69
	v_exp_f32_e32 v66, v66
	v_rcp_f32_e32 v70, v72
	s_nop 0
	v_mul_f32_e32 v65, v65, v70
	v_add_f32_e32 v66, 1.0, v66
	v_mul_f32_e32 v72, v64, v65
	v_mov_b32_e32 v70, v67
	v_pk_mul_f32 v[64:65], v[70:71], v[80:81] op_sel_hi:[1,0]
	v_mul_f32_e32 v67, 0xbfb8aa3b, v65
	v_exp_f32_e32 v67, v67
	v_rcp_f32_e32 v66, v66
	s_nop 0
	v_mul_f32_e32 v66, v69, v66
	v_add_f32_e32 v67, 1.0, v67
	v_mul_f32_e32 v66, v68, v66
	v_add_u32_e32 v80, 0x80, v144
	v_ashrrev_i32_e32 v81, 31, v80
	v_div_scale_f32 v68, vcc, 1.0, v67, 1.0
	v_rcp_f32_e32 v67, v67
	s_nop 0
	v_mul_f32_e32 v65, v65, v67
	v_mul_f32_e32 v65, v64, v65
	v_cvt_pk_bf16_f32 v64, v74, v72
	v_cvt_pk_bf16_f32 v65, v66, v65
	global_store_dwordx2 v[76:77], v[64:65], off offset:128
	v_lshlrev_b64 v[64:65], 6, v[80:81]
	v_lshl_add_u64 v[82:83], s[40:41], 0, v[64:65]
	global_load_dwordx4 v[64:67], v[82:83], off
	global_load_dwordx4 v[68:71], v[82:83], off offset:16
	global_load_dwordx4 v[72:75], v[82:83], off offset:32
	global_load_dwordx4 v[76:79], v[82:83], off offset:48
	s_waitcnt vmcnt(3)
	v_mov_b32_e32 v82, v65
	v_mov_b32_e32 v83, v66
	v_mov_b32_e32 v65, v67
	s_waitcnt vmcnt(2)
	v_mov_b32_e32 v66, v69
	v_mov_b32_e32 v67, v70
	v_mov_b32_e32 v69, v71
	v_pk_add_f32 v[64:65], v[82:83], v[64:65]
	v_pk_add_f32 v[66:67], v[66:67], v[68:69]
	v_pk_add_f32 v[64:65], v[64:65], v[64:65] op_sel:[0,1] op_sel_hi:[1,0]
	v_pk_add_f32 v[66:67], v[66:67], v[66:67] op_sel:[0,1] op_sel_hi:[1,0]
	s_waitcnt vmcnt(1)
	v_add_f32_e32 v68, v72, v73
	v_add_f32_e32 v70, v74, v75
	s_waitcnt vmcnt(0)
	v_mov_b32_e32 v65, v76
	v_mov_b32_e32 v67, v77
	v_mov_b32_e32 v69, v78
	v_mov_b32_e32 v71, v79
	v_pk_add_f32 v[64:65], v[64:65], v[66:67]
	v_pk_add_f32 v[66:67], v[68:69], v[70:71]
	s_nop 0
	v_pk_add_f32 v[64:65], v[64:65], v[66:67]
	v_mov_b32_e32 v66, v56
	v_add_f32_e32 v64, v64, v65
	v_fmamk_f32 v64, v64, 0x3a800000, v152
	v_mul_f32_e32 v65, 0x4b800000, v64
	v_cmp_gt_f32_e32 vcc, s58, v64
	v_mov_b32_e32 v67, v60
	v_mov_b32_e32 v60, v57
	v_cndmask_b32_e32 v64, v64, v65, vcc
	v_rsq_f32_e32 v64, v64
	s_nop 0
	v_mul_f32_e32 v65, 0x45800000, v64
	v_cndmask_b32_e32 v64, v64, v65, vcc
	v_pk_mul_f32 v[66:67], v[66:67], v[64:65] op_sel_hi:[1,0]
	s_nop 0
	v_mul_f32_e32 v56, 0xbfb8aa3b, v67
	v_exp_f32_e32 v56, v56
	s_nop 0
	v_add_f32_e32 v65, 1.0, v56
	v_pk_mul_f32 v[56:57], v[60:61], v[64:65] op_sel_hi:[1,0]
	v_mul_f32_e32 v60, 0xbfb8aa3b, v57
	v_exp_f32_e32 v60, v60
	s_nop 0
	v_add_f32_e32 v68, 1.0, v60
	v_rcp_f32_e32 v60, v65
	s_nop 0
	v_mul_f32_e32 v60, v67, v60
	v_mul_f32_e32 v65, v66, v60
	v_mov_b32_e32 v60, v58
	v_mov_b32_e32 v61, v62
	v_pk_mul_f32 v[60:61], v[60:61], v[64:65] op_sel_hi:[1,0]
	v_mul_f32_e32 v58, 0xbfb8aa3b, v61
	v_exp_f32_e32 v58, v58
	v_rcp_f32_e32 v62, v68
	s_nop 0
	v_mul_f32_e32 v57, v57, v62
	v_add_f32_e32 v58, 1.0, v58
	v_mul_f32_e32 v68, v56, v57
	v_mov_b32_e32 v62, v59
	v_pk_mul_f32 v[56:57], v[62:63], v[64:65] op_sel_hi:[1,0]
	v_mul_f32_e32 v59, 0xbfb8aa3b, v57
	v_exp_f32_e32 v59, v59
	v_rcp_f32_e32 v58, v58
	s_nop 0
	v_mul_f32_e32 v58, v61, v58
	v_add_f32_e32 v59, 1.0, v59
	v_mul_f32_e32 v60, v60, v58
	v_rcp_f32_e32 v58, v59
	s_nop 0
	v_mul_f32_e32 v57, v57, v58
	v_mov_b32_e32 v58, v48
	v_mov_b32_e32 v59, v52
	v_pk_mul_f32 v[58:59], v[58:59], v[64:65] op_sel_hi:[1,0]
	v_mul_f32_e32 v52, v56, v57
	v_mul_f32_e32 v48, 0xbfb8aa3b, v59
	v_exp_f32_e32 v48, v48
	v_cvt_pk_bf16_f32 v56, v65, v68
	v_cvt_pk_bf16_f32 v57, v60, v52
	v_mad_i64_i32 v[60:61], s[0:1], v80, s59, v[120:121]
	v_add_f32_e32 v62, 1.0, v48
	v_div_scale_f32 v63, s[0:1], v62, v62, 1.0
	v_rcp_f32_e32 v65, v63
	v_lshl_add_u64 v[60:61], v[60:61], 0, v[122:123]
	global_store_dwordx2 v[60:61], v[56:57], off
	v_fma_f32 v48, -v63, v65, 1.0
	v_fmac_f32_e32 v65, v48, v65
	v_mov_b32_e32 v52, v49
	v_pk_mul_f32 v[48:49], v[52:53], v[64:65] op_sel_hi:[1,0]
	v_mul_f32_e32 v52, 0xbfb8aa3b, v49
	v_exp_f32_e32 v52, v52
	s_nop 0
	v_add_f32_e32 v56, 1.0, v52
	v_rcp_f32_e32 v52, v62
	s_nop 0
	v_mul_f32_e32 v52, v59, v52
	v_mul_f32_e32 v58, v58, v52
	v_mov_b32_e32 v52, v50
	v_mov_b32_e32 v53, v54
	v_pk_mul_f32 v[52:53], v[52:53], v[64:65] op_sel_hi:[1,0]
	v_mul_f32_e32 v50, 0xbfb8aa3b, v53
	v_exp_f32_e32 v50, v50
	v_rcp_f32_e32 v54, v56
	s_nop 0
	v_mul_f32_e32 v49, v49, v54
	v_add_f32_e32 v50, 1.0, v50
	v_mul_f32_e32 v56, v48, v49
	v_mov_b32_e32 v54, v51
	v_pk_mul_f32 v[48:49], v[54:55], v[64:65] op_sel_hi:[1,0]
	v_mul_f32_e32 v51, 0xbfb8aa3b, v49
	v_exp_f32_e32 v51, v51
	v_rcp_f32_e32 v50, v50
	s_nop 0
	v_mul_f32_e32 v50, v53, v50
	v_add_f32_e32 v51, 1.0, v51
	v_mul_f32_e32 v50, v52, v50
	v_add_u32_e32 v64, 0x90, v144
	v_ashrrev_i32_e32 v65, 31, v64
	v_div_scale_f32 v52, vcc, 1.0, v51, 1.0
	v_rcp_f32_e32 v51, v51
	s_nop 0
	v_mul_f32_e32 v49, v49, v51
	v_mul_f32_e32 v49, v48, v49
	v_cvt_pk_bf16_f32 v48, v58, v56
	v_cvt_pk_bf16_f32 v49, v50, v49
	global_store_dwordx2 v[60:61], v[48:49], off offset:128
	v_lshlrev_b64 v[48:49], 6, v[64:65]
	v_lshl_add_u64 v[66:67], s[40:41], 0, v[48:49]
	global_load_dwordx4 v[48:51], v[66:67], off
	global_load_dwordx4 v[52:55], v[66:67], off offset:16
	global_load_dwordx4 v[56:59], v[66:67], off offset:32
	global_load_dwordx4 v[60:63], v[66:67], off offset:48
	s_waitcnt vmcnt(3)
	v_mov_b32_e32 v66, v49
	v_mov_b32_e32 v67, v50
	v_mov_b32_e32 v49, v51
	s_waitcnt vmcnt(2)
	v_mov_b32_e32 v50, v53
	v_mov_b32_e32 v51, v54
	v_mov_b32_e32 v53, v55
	v_pk_add_f32 v[48:49], v[66:67], v[48:49]
	v_pk_add_f32 v[50:51], v[50:51], v[52:53]
	v_pk_add_f32 v[48:49], v[48:49], v[48:49] op_sel:[0,1] op_sel_hi:[1,0]
	v_pk_add_f32 v[50:51], v[50:51], v[50:51] op_sel:[0,1] op_sel_hi:[1,0]
	s_waitcnt vmcnt(1)
	v_add_f32_e32 v52, v56, v57
	v_add_f32_e32 v54, v58, v59
	s_waitcnt vmcnt(0)
	v_mov_b32_e32 v49, v60
	v_mov_b32_e32 v51, v61
	v_mov_b32_e32 v53, v62
	v_mov_b32_e32 v55, v63
	v_pk_add_f32 v[48:49], v[48:49], v[50:51]
	v_pk_add_f32 v[50:51], v[52:53], v[54:55]
	s_nop 0
	v_pk_add_f32 v[48:49], v[48:49], v[50:51]
	v_mov_b32_e32 v50, v40
	v_add_f32_e32 v48, v48, v49
	v_fmamk_f32 v48, v48, 0x3a800000, v152
	v_mul_f32_e32 v49, 0x4b800000, v48
	v_cmp_gt_f32_e32 vcc, s58, v48
	v_mov_b32_e32 v51, v44
	v_mov_b32_e32 v44, v41
	v_cndmask_b32_e32 v48, v48, v49, vcc
	v_rsq_f32_e32 v48, v48
	s_nop 0
	v_mul_f32_e32 v49, 0x45800000, v48
	v_cndmask_b32_e32 v48, v48, v49, vcc
	v_pk_mul_f32 v[50:51], v[50:51], v[48:49] op_sel_hi:[1,0]
	s_nop 0
	v_mul_f32_e32 v40, 0xbfb8aa3b, v51
	v_exp_f32_e32 v40, v40
	s_nop 0
	v_add_f32_e32 v49, 1.0, v40
	v_pk_mul_f32 v[40:41], v[44:45], v[48:49] op_sel_hi:[1,0]
	v_mul_f32_e32 v44, 0xbfb8aa3b, v41
	v_exp_f32_e32 v44, v44
	s_nop 0
	v_add_f32_e32 v52, 1.0, v44
	v_rcp_f32_e32 v44, v49
	s_nop 0
	v_mul_f32_e32 v44, v51, v44
	v_mul_f32_e32 v49, v50, v44
	v_mov_b32_e32 v44, v42
	v_mov_b32_e32 v45, v46
	v_pk_mul_f32 v[44:45], v[44:45], v[48:49] op_sel_hi:[1,0]
	v_mul_f32_e32 v42, 0xbfb8aa3b, v45
	v_exp_f32_e32 v42, v42
	v_rcp_f32_e32 v46, v52
	s_nop 0
	v_mul_f32_e32 v41, v41, v46
	v_add_f32_e32 v42, 1.0, v42
	v_mul_f32_e32 v52, v40, v41
	v_mov_b32_e32 v46, v43
	v_pk_mul_f32 v[40:41], v[46:47], v[48:49] op_sel_hi:[1,0]
	v_mul_f32_e32 v43, 0xbfb8aa3b, v41
	v_exp_f32_e32 v43, v43
	v_rcp_f32_e32 v42, v42
	s_nop 0
	v_mul_f32_e32 v42, v45, v42
	v_add_f32_e32 v43, 1.0, v43
	v_mul_f32_e32 v44, v44, v42
	v_rcp_f32_e32 v42, v43
	s_nop 0
	v_mul_f32_e32 v41, v41, v42
	v_mov_b32_e32 v42, v32
	v_mov_b32_e32 v43, v36
	v_pk_mul_f32 v[42:43], v[42:43], v[48:49] op_sel_hi:[1,0]
	v_mul_f32_e32 v36, v40, v41
	v_mul_f32_e32 v32, 0xbfb8aa3b, v43
	v_exp_f32_e32 v32, v32
	v_cvt_pk_bf16_f32 v40, v49, v52
	v_cvt_pk_bf16_f32 v41, v44, v36
	v_mad_i64_i32 v[44:45], s[0:1], v64, s59, v[120:121]
	v_add_f32_e32 v46, 1.0, v32
	v_div_scale_f32 v47, s[0:1], v46, v46, 1.0
	v_rcp_f32_e32 v49, v47
	v_lshl_add_u64 v[44:45], v[44:45], 0, v[122:123]
	global_store_dwordx2 v[44:45], v[40:41], off
	v_fma_f32 v32, -v47, v49, 1.0
	v_fmac_f32_e32 v49, v32, v49
	v_mov_b32_e32 v36, v33
	v_pk_mul_f32 v[32:33], v[36:37], v[48:49] op_sel_hi:[1,0]
	v_mul_f32_e32 v36, 0xbfb8aa3b, v33
	v_exp_f32_e32 v36, v36
	s_nop 0
	v_add_f32_e32 v40, 1.0, v36
	v_rcp_f32_e32 v36, v46
	s_nop 0
	v_mul_f32_e32 v36, v43, v36
	v_mul_f32_e32 v42, v42, v36
	v_mov_b32_e32 v36, v34
	v_mov_b32_e32 v37, v38
	v_pk_mul_f32 v[36:37], v[36:37], v[48:49] op_sel_hi:[1,0]
	v_mul_f32_e32 v34, 0xbfb8aa3b, v37
	v_exp_f32_e32 v34, v34
	v_rcp_f32_e32 v38, v40
	s_nop 0
	v_mul_f32_e32 v33, v33, v38
	v_add_f32_e32 v34, 1.0, v34
	v_mul_f32_e32 v40, v32, v33
	v_mov_b32_e32 v38, v35
	v_pk_mul_f32 v[32:33], v[38:39], v[48:49] op_sel_hi:[1,0]
	v_mul_f32_e32 v35, 0xbfb8aa3b, v33
	v_exp_f32_e32 v35, v35
	v_rcp_f32_e32 v34, v34
	s_nop 0
	v_mul_f32_e32 v34, v37, v34
	v_add_f32_e32 v35, 1.0, v35
	v_mul_f32_e32 v34, v36, v34
	v_add_u32_e32 v48, 0xa0, v144
	v_ashrrev_i32_e32 v49, 31, v48
	v_div_scale_f32 v36, vcc, 1.0, v35, 1.0
	v_rcp_f32_e32 v35, v35
	s_nop 0
	v_mul_f32_e32 v33, v33, v35
	v_mul_f32_e32 v33, v32, v33
	v_cvt_pk_bf16_f32 v32, v42, v40
	v_cvt_pk_bf16_f32 v33, v34, v33
	global_store_dwordx2 v[44:45], v[32:33], off offset:128
	v_lshlrev_b64 v[32:33], 6, v[48:49]
	v_lshl_add_u64 v[50:51], s[40:41], 0, v[32:33]
	global_load_dwordx4 v[32:35], v[50:51], off
	global_load_dwordx4 v[36:39], v[50:51], off offset:16
	global_load_dwordx4 v[40:43], v[50:51], off offset:32
	global_load_dwordx4 v[44:47], v[50:51], off offset:48
	s_waitcnt vmcnt(3)
	v_mov_b32_e32 v50, v33
	v_mov_b32_e32 v51, v34
	v_mov_b32_e32 v33, v35
	s_waitcnt vmcnt(2)
	v_mov_b32_e32 v34, v37
	v_mov_b32_e32 v35, v38
	v_mov_b32_e32 v37, v39
	v_pk_add_f32 v[32:33], v[50:51], v[32:33]
	v_pk_add_f32 v[34:35], v[34:35], v[36:37]
	v_pk_add_f32 v[32:33], v[32:33], v[32:33] op_sel:[0,1] op_sel_hi:[1,0]
	v_pk_add_f32 v[34:35], v[34:35], v[34:35] op_sel:[0,1] op_sel_hi:[1,0]
	s_waitcnt vmcnt(1)
	v_add_f32_e32 v36, v40, v41
	v_add_f32_e32 v38, v42, v43
	s_waitcnt vmcnt(0)
	v_mov_b32_e32 v33, v44
	v_mov_b32_e32 v35, v45
	v_mov_b32_e32 v37, v46
	v_mov_b32_e32 v39, v47
	v_pk_add_f32 v[32:33], v[32:33], v[34:35]
	v_pk_add_f32 v[34:35], v[36:37], v[38:39]
	s_nop 0
	v_pk_add_f32 v[32:33], v[32:33], v[34:35]
	v_mov_b32_e32 v34, v24
	v_add_f32_e32 v32, v32, v33
	v_fmamk_f32 v32, v32, 0x3a800000, v152
	v_mul_f32_e32 v33, 0x4b800000, v32
	v_cmp_gt_f32_e32 vcc, s58, v32
	v_mov_b32_e32 v35, v28
	v_mov_b32_e32 v28, v25
	v_cndmask_b32_e32 v32, v32, v33, vcc
	v_rsq_f32_e32 v32, v32
	s_nop 0
	v_mul_f32_e32 v33, 0x45800000, v32
	v_cndmask_b32_e32 v32, v32, v33, vcc
	v_pk_mul_f32 v[34:35], v[34:35], v[32:33] op_sel_hi:[1,0]
	s_nop 0
	v_mul_f32_e32 v24, 0xbfb8aa3b, v35
	v_exp_f32_e32 v24, v24
	s_nop 0
	v_add_f32_e32 v33, 1.0, v24
	v_pk_mul_f32 v[24:25], v[28:29], v[32:33] op_sel_hi:[1,0]
	v_mul_f32_e32 v28, 0xbfb8aa3b, v25
	v_exp_f32_e32 v28, v28
	s_nop 0
	v_add_f32_e32 v36, 1.0, v28
	v_rcp_f32_e32 v28, v33
	s_nop 0
	v_mul_f32_e32 v28, v35, v28
	v_mul_f32_e32 v33, v34, v28
	v_mov_b32_e32 v28, v26
	v_mov_b32_e32 v29, v30
	v_pk_mul_f32 v[28:29], v[28:29], v[32:33] op_sel_hi:[1,0]
	v_mul_f32_e32 v26, 0xbfb8aa3b, v29
	v_exp_f32_e32 v26, v26
	v_rcp_f32_e32 v30, v36
	s_nop 0
	v_mul_f32_e32 v25, v25, v30
	v_add_f32_e32 v26, 1.0, v26
	v_mul_f32_e32 v36, v24, v25
	v_mov_b32_e32 v30, v27
	v_pk_mul_f32 v[24:25], v[30:31], v[32:33] op_sel_hi:[1,0]
	v_mul_f32_e32 v27, 0xbfb8aa3b, v25
	v_exp_f32_e32 v27, v27
	v_rcp_f32_e32 v26, v26
	s_nop 0
	v_mul_f32_e32 v26, v29, v26
	v_add_f32_e32 v27, 1.0, v27
	v_mul_f32_e32 v28, v28, v26
	v_rcp_f32_e32 v26, v27
	s_nop 0
	v_mul_f32_e32 v25, v25, v26
	v_mov_b32_e32 v26, v16
	v_mov_b32_e32 v27, v20
	v_pk_mul_f32 v[26:27], v[26:27], v[32:33] op_sel_hi:[1,0]
	v_mul_f32_e32 v20, v24, v25
	v_mul_f32_e32 v16, 0xbfb8aa3b, v27
	v_exp_f32_e32 v16, v16
	v_cvt_pk_bf16_f32 v24, v33, v36
	v_cvt_pk_bf16_f32 v25, v28, v20
	v_mad_i64_i32 v[28:29], s[0:1], v48, s59, v[120:121]
	v_add_f32_e32 v30, 1.0, v16
	v_div_scale_f32 v31, s[0:1], v30, v30, 1.0
	v_rcp_f32_e32 v33, v31
	v_lshl_add_u64 v[28:29], v[28:29], 0, v[122:123]
	global_store_dwordx2 v[28:29], v[24:25], off
	v_fma_f32 v16, -v31, v33, 1.0
	v_fmac_f32_e32 v33, v16, v33
	v_mov_b32_e32 v20, v17
	v_pk_mul_f32 v[16:17], v[20:21], v[32:33] op_sel_hi:[1,0]
	v_mul_f32_e32 v20, 0xbfb8aa3b, v17
	v_exp_f32_e32 v20, v20
	s_nop 0
	v_add_f32_e32 v24, 1.0, v20
	v_rcp_f32_e32 v20, v30
	s_nop 0
	v_mul_f32_e32 v20, v27, v20
	v_mul_f32_e32 v26, v26, v20
	v_mov_b32_e32 v20, v18
	v_mov_b32_e32 v21, v22
	v_pk_mul_f32 v[20:21], v[20:21], v[32:33] op_sel_hi:[1,0]
	v_mul_f32_e32 v18, 0xbfb8aa3b, v21
	v_exp_f32_e32 v18, v18
	v_rcp_f32_e32 v22, v24
	s_nop 0
	v_mul_f32_e32 v17, v17, v22
	v_add_f32_e32 v18, 1.0, v18
	v_mul_f32_e32 v24, v16, v17
	v_mov_b32_e32 v22, v19
	v_pk_mul_f32 v[16:17], v[22:23], v[32:33] op_sel_hi:[1,0]
	v_mul_f32_e32 v19, 0xbfb8aa3b, v17
	v_exp_f32_e32 v19, v19
	v_rcp_f32_e32 v18, v18
	s_nop 0
	v_mul_f32_e32 v18, v21, v18
	v_add_f32_e32 v19, 1.0, v19
	v_mul_f32_e32 v18, v20, v18
	v_add_u32_e32 v32, 0xb0, v144
	v_ashrrev_i32_e32 v33, 31, v32
	v_div_scale_f32 v20, vcc, 1.0, v19, 1.0
	v_rcp_f32_e32 v19, v19
	s_nop 0
	v_mul_f32_e32 v17, v17, v19
	v_mul_f32_e32 v17, v16, v17
	v_cvt_pk_bf16_f32 v16, v26, v24
	v_cvt_pk_bf16_f32 v17, v18, v17
	global_store_dwordx2 v[28:29], v[16:17], off offset:128
	v_lshlrev_b64 v[16:17], 6, v[32:33]
	v_lshl_add_u64 v[34:35], s[40:41], 0, v[16:17]
	global_load_dwordx4 v[16:19], v[34:35], off
	global_load_dwordx4 v[20:23], v[34:35], off offset:16
	global_load_dwordx4 v[24:27], v[34:35], off offset:32
	global_load_dwordx4 v[28:31], v[34:35], off offset:48
	s_waitcnt vmcnt(3)
	v_mov_b32_e32 v34, v17
	v_mov_b32_e32 v35, v18
	v_mov_b32_e32 v17, v19
	s_waitcnt vmcnt(2)
	v_mov_b32_e32 v18, v21
	v_mov_b32_e32 v19, v22
	v_mov_b32_e32 v21, v23
	v_pk_add_f32 v[16:17], v[34:35], v[16:17]
	v_pk_add_f32 v[18:19], v[18:19], v[20:21]
	v_pk_add_f32 v[16:17], v[16:17], v[16:17] op_sel:[0,1] op_sel_hi:[1,0]
	v_pk_add_f32 v[18:19], v[18:19], v[18:19] op_sel:[0,1] op_sel_hi:[1,0]
	s_waitcnt vmcnt(1)
	v_add_f32_e32 v20, v24, v25
	v_add_f32_e32 v22, v26, v27
	s_waitcnt vmcnt(0)
	v_mov_b32_e32 v17, v28
	v_mov_b32_e32 v19, v29
	v_mov_b32_e32 v21, v30
	v_mov_b32_e32 v23, v31
	v_pk_add_f32 v[16:17], v[16:17], v[18:19]
	v_pk_add_f32 v[18:19], v[20:21], v[22:23]
	s_nop 0
	v_pk_add_f32 v[16:17], v[16:17], v[18:19]
	v_mov_b32_e32 v18, v8
	v_add_f32_e32 v16, v16, v17
	v_fmamk_f32 v16, v16, 0x3a800000, v152
	v_mul_f32_e32 v17, 0x4b800000, v16
	v_cmp_gt_f32_e32 vcc, s58, v16
	v_mov_b32_e32 v19, v12
	v_mov_b32_e32 v12, v9
	v_cndmask_b32_e32 v16, v16, v17, vcc
	v_rsq_f32_e32 v16, v16
	s_nop 0
	v_mul_f32_e32 v17, 0x45800000, v16
	v_cndmask_b32_e32 v16, v16, v17, vcc
	v_pk_mul_f32 v[18:19], v[18:19], v[16:17] op_sel_hi:[1,0]
	s_nop 0
	v_mul_f32_e32 v8, 0xbfb8aa3b, v19
	v_exp_f32_e32 v8, v8
	s_nop 0
	v_add_f32_e32 v17, 1.0, v8
	v_pk_mul_f32 v[8:9], v[12:13], v[16:17] op_sel_hi:[1,0]
	v_mul_f32_e32 v12, 0xbfb8aa3b, v9
	v_exp_f32_e32 v12, v12
	s_nop 0
	v_add_f32_e32 v20, 1.0, v12
	v_rcp_f32_e32 v12, v17
	s_nop 0
	v_mul_f32_e32 v12, v19, v12
	v_mul_f32_e32 v17, v18, v12
	v_mov_b32_e32 v12, v10
	v_mov_b32_e32 v13, v14
	v_pk_mul_f32 v[12:13], v[12:13], v[16:17] op_sel_hi:[1,0]
	v_mul_f32_e32 v10, 0xbfb8aa3b, v13
	v_exp_f32_e32 v10, v10
	v_rcp_f32_e32 v14, v20
	s_nop 0
	v_mul_f32_e32 v9, v9, v14
	v_add_f32_e32 v10, 1.0, v10
	v_mul_f32_e32 v20, v8, v9
	v_mov_b32_e32 v14, v11
	v_pk_mul_f32 v[8:9], v[14:15], v[16:17] op_sel_hi:[1,0]
	v_mul_f32_e32 v11, 0xbfb8aa3b, v9
	v_exp_f32_e32 v11, v11
	v_rcp_f32_e32 v10, v10
	s_nop 0
	v_mul_f32_e32 v10, v13, v10
	v_add_f32_e32 v11, 1.0, v11
	v_mul_f32_e32 v12, v12, v10
	v_rcp_f32_e32 v10, v11
	s_nop 0
	v_mul_f32_e32 v9, v9, v10
	v_mov_b32_e32 v10, v0
	v_mov_b32_e32 v11, v4
	v_pk_mul_f32 v[10:11], v[10:11], v[16:17] op_sel_hi:[1,0]
	v_mul_f32_e32 v4, v8, v9
	v_mul_f32_e32 v0, 0xbfb8aa3b, v11
	v_exp_f32_e32 v0, v0
	v_cvt_pk_bf16_f32 v8, v17, v20
	v_cvt_pk_bf16_f32 v9, v12, v4
	v_mad_i64_i32 v[12:13], s[0:1], v32, s59, v[120:121]
	v_add_f32_e32 v14, 1.0, v0
	v_div_scale_f32 v15, s[0:1], v14, v14, 1.0
	v_rcp_f32_e32 v17, v15
	v_lshl_add_u64 v[12:13], v[12:13], 0, v[122:123]
	global_store_dwordx2 v[12:13], v[8:9], off
	v_fma_f32 v0, -v15, v17, 1.0
	v_fmac_f32_e32 v17, v0, v17
	v_mov_b32_e32 v4, v1
	v_pk_mul_f32 v[0:1], v[4:5], v[16:17] op_sel_hi:[1,0]
	v_mul_f32_e32 v4, 0xbfb8aa3b, v1
	v_exp_f32_e32 v4, v4
	s_nop 0
	v_add_f32_e32 v8, 1.0, v4
	v_rcp_f32_e32 v4, v14
	s_nop 0
	v_mul_f32_e32 v4, v11, v4
	v_mul_f32_e32 v10, v10, v4
	v_mov_b32_e32 v4, v2
	v_mov_b32_e32 v5, v6
	v_pk_mul_f32 v[4:5], v[4:5], v[16:17] op_sel_hi:[1,0]
	v_mul_f32_e32 v2, 0xbfb8aa3b, v5
	v_exp_f32_e32 v2, v2
	v_rcp_f32_e32 v6, v8
	s_nop 0
	v_mul_f32_e32 v1, v1, v6
	v_add_f32_e32 v2, 1.0, v2
	v_mul_f32_e32 v8, v0, v1
	v_mov_b32_e32 v6, v3
	v_pk_mul_f32 v[0:1], v[6:7], v[16:17] op_sel_hi:[1,0]
	v_mul_f32_e32 v3, 0xbfb8aa3b, v1
	v_exp_f32_e32 v3, v3
	v_rcp_f32_e32 v2, v2
	s_nop 0
	v_mul_f32_e32 v2, v5, v2
	v_add_f32_e32 v3, 1.0, v3
	v_mul_f32_e32 v2, v4, v2
	v_rcp_f32_e32 v3, v3
	s_nop 0
	v_mul_f32_e32 v1, v1, v3
	v_mul_f32_e32 v1, v0, v1
	s_andn2_b64 vcc, exec, s[6:7]
	s_mov_b64 s[6:7], -1
	v_cvt_pk_bf16_f32 v0, v10, v8
	v_cvt_pk_bf16_f32 v1, v2, v1
	global_store_dwordx2 v[12:13], v[0:1], off offset:128
	s_cbranch_vccnz .LBB0_543
	s_andn2_b64 vcc, exec, s[14:15]
	s_cbranch_vccnz .LBB0_542
	s_barrier
	s_branch .LBB0_542
